# P0 row loop: x->bf16 conversion with v_cvt_pk_bf16_f32 (same round-to-nearest-even) instead of the 6-instruction bit trick per pair
# speedup vs baseline: 1.0007x; 1.0007x over previous
.LBB0_26:
	s_or_b64 exec, exec, s[60:61]
	v_lshl_add_u64 v[56:57], s[72:73], 0, v[40:41]
	v_add_co_u32_e32 v60, vcc, s33, v56
	s_nop 1
	v_addc_co_u32_e32 v61, vcc, 0, v57, vcc
	v_cvt_pk_bf16_f32 v58, v30, v31
	v_cvt_pk_bf16_f32 v59, v32, v33
	v_cvt_pk_bf16_f32 v56, v26, v27
	v_cvt_pk_bf16_f32 v57, v28, v29
	global_store_dwordx2 v[60:61], v[56:57], off offset:512
	global_store_dwordx2 v[60:61], v[58:59], off
	v_cvt_pk_bf16_f32 v56, v22, v23
	v_cvt_pk_bf16_f32 v57, v24, v25
	global_store_dwordx2 v[60:61], v[56:57], off offset:1024
	v_cvt_pk_bf16_f32 v62, v18, v19
	v_cvt_pk_bf16_f32 v63, v20, v21
	global_store_dwordx2 v[60:61], v[62:63], off offset:1536
	ds_read_b128 v[56:59], v51
	ds_read_b128 v[60:63], v51 offset:1024
	s_waitcnt lgkmcnt(1)
	v_mul_f32_e32 v55, v31, v57
	v_fmac_f32_e32 v55, v30, v56
	v_mul_f32_e32 v56, v33, v59
	v_fmac_f32_e32 v56, v32, v58
	s_waitcnt lgkmcnt(0)
	v_mul_f32_e32 v61, v27, v61
	v_add_f32_e32 v55, v55, v56
	v_fmac_f32_e32 v61, v26, v60
	v_mul_f32_e32 v60, v29, v63
	ds_read_b128 v[56:59], v51 offset:2048
	v_fmac_f32_e32 v60, v28, v62
	v_add_f32_e32 v55, 0, v55
	v_add_f32_e32 v60, v61, v60
	v_add_f32_e32 v55, v55, v60
	ds_read_b128 v[60:63], v51 offset:3072
	s_waitcnt lgkmcnt(1)
	v_mul_f32_e32 v57, v23, v57
	v_fmac_f32_e32 v57, v22, v56
	v_mul_f32_e32 v56, v25, v59
	v_fmac_f32_e32 v56, v24, v58
	v_add_f32_e32 v56, v57, v56
	s_waitcnt lgkmcnt(0)
	v_mul_f32_e32 v64, v19, v61
	v_mul_f32_e32 v65, v21, v63
	v_add_f32_e32 v55, v55, v56
	v_fmac_f32_e32 v64, v18, v60
	v_fmac_f32_e32 v65, v20, v62
	ds_read_b128 v[56:59], v51 offset:5120
	ds_read_b128 v[60:63], v51 offset:4096
	v_add_f32_e32 v64, v64, v65
	v_add_f32_e32 v55, v55, v64
	ds_read_b128 v[64:67], v51 offset:7168
	ds_read_b128 v[68:71], v51 offset:6144
	s_waitcnt lgkmcnt(3)
	v_mul_f32_e32 v57, v27, v57
	s_waitcnt lgkmcnt(2)
	v_mul_f32_e32 v61, v31, v61
	v_fmac_f32_e32 v61, v30, v60
	v_mul_f32_e32 v60, v33, v63
	v_fmac_f32_e32 v57, v26, v56
	v_mul_f32_e32 v56, v29, v59
	v_fmac_f32_e32 v60, v32, v62
	v_fmac_f32_e32 v56, v28, v58
	v_add_f32_e32 v60, v61, v60
	v_add_f32_e32 v56, v57, v56
	s_waitcnt lgkmcnt(0)
	v_mul_f32_e32 v57, v23, v69
	v_mul_f32_e32 v58, v25, v71
	v_add_f32_e32 v60, 0, v60
	v_fmac_f32_e32 v57, v22, v68
	v_fmac_f32_e32 v58, v24, v70
	v_add_f32_e32 v56, v60, v56
	v_add_f32_e32 v57, v57, v58
	v_add_f32_e32 v56, v56, v57
	v_mul_f32_e32 v57, v19, v65
	v_fmac_f32_e32 v57, v18, v64
	ds_read_b128 v[58:61], v51 offset:9216
	ds_read_b128 v[62:65], v51 offset:8192
	v_mul_f32_e32 v67, v21, v67
	v_fmac_f32_e32 v67, v20, v66
	v_add_f32_e32 v57, v57, v67
	v_add_f32_e32 v56, v56, v57
	ds_read_b128 v[66:69], v51 offset:11264
	ds_read_b128 v[70:73], v51 offset:10240
	s_waitcnt lgkmcnt(2)
	v_mul_f32_e32 v57, v31, v63
	v_fmac_f32_e32 v57, v30, v62
	v_mul_f32_e32 v62, v33, v65
	v_mul_f32_e32 v59, v27, v59
	v_fmac_f32_e32 v62, v32, v64
	v_fmac_f32_e32 v59, v26, v58
	v_mul_f32_e32 v58, v29, v61
	v_add_f32_e32 v57, v57, v62
	v_fmac_f32_e32 v58, v28, v60
	v_add_f32_e32 v57, 0, v57
	v_add_f32_e32 v58, v59, v58
	v_add_f32_e32 v57, v57, v58
	s_waitcnt lgkmcnt(0)
	v_mul_f32_e32 v58, v23, v71
	v_mul_f32_e32 v59, v25, v73
	v_fmac_f32_e32 v58, v22, v70
	v_fmac_f32_e32 v59, v24, v72
	v_add_f32_e32 v58, v58, v59
	v_mul_f32_e32 v67, v19, v67
	v_add_f32_e32 v57, v57, v58
	v_fmac_f32_e32 v67, v18, v66
	v_mul_f32_e32 v66, v21, v69
	ds_read_b128 v[58:61], v51 offset:13312
	ds_read_b128 v[62:65], v51 offset:12288
	v_fmac_f32_e32 v66, v20, v68
	v_add_f32_e32 v66, v67, v66
	v_add_f32_e32 v57, v57, v66
	ds_read_b128 v[66:69], v51 offset:15360
	ds_read_b128 v[70:73], v51 offset:14336
	s_waitcnt lgkmcnt(2)
	v_mul_f32_e32 v63, v31, v63
	v_mul_f32_e32 v59, v27, v59
	v_fmac_f32_e32 v63, v30, v62
	v_mul_f32_e32 v62, v33, v65
	v_fmac_f32_e32 v59, v26, v58
	v_mul_f32_e32 v58, v29, v61
	v_fmac_f32_e32 v62, v32, v64
	v_fmac_f32_e32 v58, v28, v60
	v_add_f32_e32 v62, v63, v62
	v_add_f32_e32 v58, v59, v58
	s_waitcnt lgkmcnt(0)
	v_mul_f32_e32 v59, v23, v71
	v_mul_f32_e32 v60, v25, v73
	v_add_f32_e32 v62, 0, v62
	v_fmac_f32_e32 v59, v22, v70
	v_fmac_f32_e32 v60, v24, v72
	v_add_f32_e32 v58, v62, v58
	v_add_f32_e32 v59, v59, v60
	v_add_f32_e32 v58, v58, v59
	v_mul_f32_e32 v59, v19, v67
	v_mul_f32_e32 v64, v21, v69
	ds_read_b128 v[60:63], v51 offset:16384
	v_fmac_f32_e32 v59, v18, v66
	v_fmac_f32_e32 v64, v20, v68
	v_add_f32_e32 v59, v59, v64
	ds_read_b128 v[64:67], v51 offset:17408
	v_add_f32_e32 v58, v58, v59
	s_waitcnt lgkmcnt(1)
	v_mul_f32_e32 v59, v31, v61
	v_fmac_f32_e32 v59, v30, v60
	v_mul_f32_e32 v60, v33, v63
	v_fmac_f32_e32 v60, v32, v62
	s_waitcnt lgkmcnt(0)
	v_mul_f32_e32 v65, v27, v65
	v_add_f32_e32 v59, v59, v60
	v_fmac_f32_e32 v65, v26, v64
	v_mul_f32_e32 v64, v29, v67
	ds_read_b128 v[60:63], v51 offset:18432
	v_fmac_f32_e32 v64, v28, v66
	v_add_f32_e32 v59, 0, v59
	v_add_f32_e32 v64, v65, v64
	v_add_f32_e32 v59, v59, v64
	ds_read_b128 v[64:67], v51 offset:19456
	s_waitcnt lgkmcnt(1)
	v_mul_f32_e32 v61, v23, v61
	v_fmac_f32_e32 v61, v22, v60
	v_mul_f32_e32 v60, v25, v63
	v_fmac_f32_e32 v60, v24, v62
	v_add_f32_e32 v60, v61, v60
	s_waitcnt lgkmcnt(0)
	v_mul_f32_e32 v68, v19, v65
	v_mul_f32_e32 v69, v21, v67
	v_add_f32_e32 v59, v59, v60
	v_fmac_f32_e32 v68, v18, v64
	v_fmac_f32_e32 v69, v20, v66
	ds_read_b128 v[60:63], v51 offset:21504
	ds_read_b128 v[64:67], v51 offset:20480
	v_add_f32_e32 v68, v68, v69
	v_add_f32_e32 v59, v59, v68
	ds_read_b128 v[68:71], v51 offset:23552
	ds_read_b128 v[72:75], v51 offset:22528
	s_waitcnt lgkmcnt(3)
	v_mul_f32_e32 v61, v27, v61
	s_waitcnt lgkmcnt(2)
	v_mul_f32_e32 v65, v31, v65
	v_fmac_f32_e32 v65, v30, v64
	v_mul_f32_e32 v64, v33, v67
	v_fmac_f32_e32 v61, v26, v60
	v_mul_f32_e32 v60, v29, v63
	v_fmac_f32_e32 v64, v32, v66
	v_fmac_f32_e32 v60, v28, v62
	v_add_f32_e32 v64, v65, v64
	v_add_f32_e32 v60, v61, v60
	s_waitcnt lgkmcnt(0)
	v_mul_f32_e32 v61, v23, v73
	v_mul_f32_e32 v62, v25, v75
	v_add_f32_e32 v64, 0, v64
	v_fmac_f32_e32 v61, v22, v72
	v_fmac_f32_e32 v62, v24, v74
	v_add_f32_e32 v60, v64, v60
	v_add_f32_e32 v61, v61, v62
	v_mul_f32_e32 v69, v19, v69
	v_add_f32_e32 v72, v60, v61
	v_fmac_f32_e32 v69, v18, v68
	v_mul_f32_e32 v68, v21, v71
	ds_read_b128 v[60:63], v51 offset:25600
	ds_read_b128 v[64:67], v51 offset:24576
	v_fmac_f32_e32 v68, v20, v70
	v_add_f32_e32 v68, v69, v68
	v_add_f32_e32 v76, v72, v68
	ds_read_b128 v[68:71], v51 offset:27648
	ds_read_b128 v[72:75], v51 offset:26624
	s_waitcnt lgkmcnt(2)
	v_mul_f32_e32 v65, v31, v65
	v_mul_f32_e32 v61, v27, v61
	v_fmac_f32_e32 v65, v30, v64
	v_mul_f32_e32 v64, v33, v67
	v_fmac_f32_e32 v61, v26, v60
	v_mul_f32_e32 v60, v29, v63
	v_fmac_f32_e32 v64, v32, v66
	v_fmac_f32_e32 v60, v28, v62
	v_add_f32_e32 v64, v65, v64
	v_add_f32_e32 v60, v61, v60
	s_waitcnt lgkmcnt(0)
	v_mul_f32_e32 v61, v23, v73
	v_mul_f32_e32 v62, v25, v75
	v_add_f32_e32 v64, 0, v64
	v_fmac_f32_e32 v61, v22, v72
	v_fmac_f32_e32 v62, v24, v74
	v_add_f32_e32 v60, v64, v60
	v_add_f32_e32 v61, v61, v62
	v_mul_f32_e32 v69, v19, v69
	v_add_f32_e32 v72, v60, v61
	v_fmac_f32_e32 v69, v18, v68
	v_mul_f32_e32 v68, v21, v71
	ds_read_b128 v[60:63], v51 offset:29696
	ds_read_b128 v[64:67], v51 offset:28672
	v_fmac_f32_e32 v68, v20, v70
	v_add_f32_e32 v68, v69, v68
	v_add_f32_e32 v77, v72, v68
	ds_read_b128 v[68:71], v51 offset:31744
	ds_read_b128 v[72:75], v51 offset:30720
	s_waitcnt lgkmcnt(2)
	v_mul_f32_e32 v65, v31, v65
	v_mul_f32_e32 v61, v27, v61
	v_fmac_f32_e32 v65, v30, v64
	v_mul_f32_e32 v64, v33, v67
	v_fmac_f32_e32 v61, v26, v60
	v_mul_f32_e32 v60, v29, v63
	v_fmac_f32_e32 v64, v32, v66
	v_fmac_f32_e32 v60, v28, v62
	v_add_f32_e32 v64, v65, v64
	v_add_f32_e32 v60, v61, v60
	s_waitcnt lgkmcnt(0)
	v_mul_f32_e32 v61, v23, v73
	v_mul_f32_e32 v62, v25, v75
	v_add_f32_e32 v64, 0, v64
	v_fmac_f32_e32 v61, v22, v72
	v_fmac_f32_e32 v62, v24, v74
	v_add_f32_e32 v60, v64, v60
	v_add_f32_e32 v61, v61, v62
	v_add_f32_e32 v64, v60, v61
	v_mul_f32_e32 v65, v19, v69
	v_mul_f32_e32 v66, v21, v71
	ds_read_b128 v[60:63], v51 offset:32768
	v_fmac_f32_e32 v65, v18, v68
	v_fmac_f32_e32 v66, v20, v70
	v_add_f32_e32 v65, v65, v66
	v_add_f32_e32 v78, v64, v65
	ds_read_b128 v[64:67], v51 offset:33792
	s_waitcnt lgkmcnt(1)
	v_mul_f32_e32 v61, v31, v61
	v_fmac_f32_e32 v61, v30, v60
	v_mul_f32_e32 v60, v33, v63
	v_fmac_f32_e32 v60, v32, v62
	v_add_f32_e32 v60, v61, v60
	s_waitcnt lgkmcnt(0)
	v_mul_f32_e32 v65, v27, v65
	v_add_f32_e32 v68, 0, v60
	v_fmac_f32_e32 v65, v26, v64
	v_mul_f32_e32 v64, v29, v67
	ds_read_b128 v[60:63], v51 offset:34816
	v_fmac_f32_e32 v64, v28, v66
	v_add_f32_e32 v64, v65, v64
	v_add_f32_e32 v68, v68, v64
	ds_read_b128 v[64:67], v51 offset:35840
	s_waitcnt lgkmcnt(1)
	v_mul_f32_e32 v61, v23, v61
	v_fmac_f32_e32 v61, v22, v60
	v_mul_f32_e32 v60, v25, v63
	v_fmac_f32_e32 v60, v24, v62
	v_add_f32_e32 v60, v61, v60
	s_waitcnt lgkmcnt(0)
	v_mul_f32_e32 v69, v19, v65
	v_mul_f32_e32 v70, v21, v67
	v_add_f32_e32 v68, v68, v60
	v_fmac_f32_e32 v69, v18, v64
	v_fmac_f32_e32 v70, v20, v66
	ds_read_b128 v[60:63], v51 offset:37888
	ds_read_b128 v[64:67], v51 offset:36864
	v_add_f32_e32 v69, v69, v70
	v_add_f32_e32 v79, v68, v69
	ds_read_b128 v[68:71], v51 offset:39936
	ds_read_b128 v[72:75], v51 offset:38912
	s_waitcnt lgkmcnt(3)
	v_mul_f32_e32 v61, v27, v61
	s_waitcnt lgkmcnt(2)
	v_mul_f32_e32 v65, v31, v65
	v_fmac_f32_e32 v65, v30, v64
	v_mul_f32_e32 v64, v33, v67
	v_fmac_f32_e32 v61, v26, v60
	v_mul_f32_e32 v60, v29, v63
	v_fmac_f32_e32 v64, v32, v66
	v_fmac_f32_e32 v60, v28, v62
	v_add_f32_e32 v64, v65, v64
	v_add_f32_e32 v60, v61, v60
	s_waitcnt lgkmcnt(0)
	v_mul_f32_e32 v61, v23, v73
	v_mul_f32_e32 v62, v25, v75
	v_add_f32_e32 v64, 0, v64
	v_fmac_f32_e32 v61, v22, v72
	v_fmac_f32_e32 v62, v24, v74
	v_add_f32_e32 v60, v64, v60
	v_add_f32_e32 v61, v61, v62
	v_mul_f32_e32 v69, v19, v69
	v_add_f32_e32 v72, v60, v61
	v_fmac_f32_e32 v69, v18, v68
	v_mul_f32_e32 v68, v21, v71
	ds_read_b128 v[60:63], v51 offset:41984
	ds_read_b128 v[64:67], v51 offset:40960
	v_fmac_f32_e32 v68, v20, v70
	v_add_f32_e32 v68, v69, v68
	v_add_f32_e32 v80, v72, v68
	ds_read_b128 v[68:71], v51 offset:44032
	ds_read_b128 v[72:75], v51 offset:43008
	s_waitcnt lgkmcnt(2)
	v_mul_f32_e32 v65, v31, v65
	v_mul_f32_e32 v61, v27, v61
	v_fmac_f32_e32 v65, v30, v64
	v_mul_f32_e32 v64, v33, v67
	v_fmac_f32_e32 v61, v26, v60
	v_mul_f32_e32 v60, v29, v63
	v_fmac_f32_e32 v64, v32, v66
	v_fmac_f32_e32 v60, v28, v62
	v_add_f32_e32 v64, v65, v64
	v_add_f32_e32 v60, v61, v60
	s_waitcnt lgkmcnt(0)
	v_mul_f32_e32 v61, v23, v73
	v_mul_f32_e32 v62, v25, v75
	v_add_f32_e32 v64, 0, v64
	v_fmac_f32_e32 v61, v22, v72
	v_fmac_f32_e32 v62, v24, v74
	v_add_f32_e32 v60, v64, v60
	v_add_f32_e32 v61, v61, v62
	v_mul_f32_e32 v69, v19, v69
	v_add_f32_e32 v72, v60, v61
	v_fmac_f32_e32 v69, v18, v68
	v_mul_f32_e32 v68, v21, v71
	ds_read_b128 v[60:63], v51 offset:46080
	ds_read_b128 v[64:67], v51 offset:45056
	v_fmac_f32_e32 v68, v20, v70
	v_add_f32_e32 v68, v69, v68
	v_add_f32_e32 v81, v72, v68
	ds_read_b128 v[68:71], v51 offset:48128
	ds_read_b128 v[72:75], v51 offset:47104
	s_waitcnt lgkmcnt(2)
	v_mul_f32_e32 v65, v31, v65
	v_mul_f32_e32 v61, v27, v61
	v_fmac_f32_e32 v65, v30, v64
	v_mul_f32_e32 v64, v33, v67
	v_fmac_f32_e32 v61, v26, v60
	v_mul_f32_e32 v60, v29, v63
	v_fmac_f32_e32 v64, v32, v66
	v_fmac_f32_e32 v60, v28, v62
	v_add_f32_e32 v64, v65, v64
	v_add_f32_e32 v60, v61, v60
	s_waitcnt lgkmcnt(0)
	v_mul_f32_e32 v61, v23, v73
	v_mul_f32_e32 v62, v25, v75
	v_add_f32_e32 v64, 0, v64
	v_fmac_f32_e32 v61, v22, v72
	v_fmac_f32_e32 v62, v24, v74
	v_add_f32_e32 v60, v64, v60
	v_add_f32_e32 v61, v61, v62
	v_add_f32_e32 v64, v60, v61
	v_mul_f32_e32 v65, v19, v69
	v_mul_f32_e32 v66, v21, v71
	ds_read_b128 v[60:63], v51 offset:49152
	v_fmac_f32_e32 v65, v18, v68
	v_fmac_f32_e32 v66, v20, v70
	v_add_f32_e32 v65, v65, v66
	v_add_f32_e32 v82, v64, v65
	ds_read_b128 v[64:67], v51 offset:50176
	s_waitcnt lgkmcnt(1)
	v_mul_f32_e32 v61, v31, v61
	v_fmac_f32_e32 v61, v30, v60
	v_mul_f32_e32 v60, v33, v63
	v_fmac_f32_e32 v60, v32, v62
	v_add_f32_e32 v60, v61, v60
	s_waitcnt lgkmcnt(0)
	v_mul_f32_e32 v65, v27, v65
	v_add_f32_e32 v68, 0, v60
	v_fmac_f32_e32 v65, v26, v64
	v_mul_f32_e32 v64, v29, v67
	ds_read_b128 v[60:63], v51 offset:51200
	v_fmac_f32_e32 v64, v28, v66
	v_add_f32_e32 v64, v65, v64
	v_add_f32_e32 v68, v68, v64
	ds_read_b128 v[64:67], v51 offset:52224
	s_waitcnt lgkmcnt(1)
	v_mul_f32_e32 v61, v23, v61
	v_fmac_f32_e32 v61, v22, v60
	v_mul_f32_e32 v60, v25, v63
	v_fmac_f32_e32 v60, v24, v62
	v_add_f32_e32 v60, v61, v60
	s_waitcnt lgkmcnt(0)
	v_mul_f32_e32 v69, v19, v65
	v_mul_f32_e32 v70, v21, v67
	v_add_f32_e32 v68, v68, v60
	v_fmac_f32_e32 v69, v18, v64
	v_fmac_f32_e32 v70, v20, v66
	ds_read_b128 v[60:63], v51 offset:54272
	ds_read_b128 v[64:67], v51 offset:53248
	v_add_f32_e32 v69, v69, v70
	v_add_f32_e32 v83, v68, v69
	ds_read_b128 v[68:71], v51 offset:56320
	ds_read_b128 v[72:75], v51 offset:55296
	s_waitcnt lgkmcnt(3)
	v_mul_f32_e32 v61, v27, v61
	s_waitcnt lgkmcnt(2)
	v_mul_f32_e32 v65, v31, v65
	v_fmac_f32_e32 v65, v30, v64
	v_mul_f32_e32 v64, v33, v67
	v_fmac_f32_e32 v61, v26, v60
	v_mul_f32_e32 v60, v29, v63
	v_fmac_f32_e32 v64, v32, v66
	v_fmac_f32_e32 v60, v28, v62
	v_add_f32_e32 v64, v65, v64
	v_add_f32_e32 v60, v61, v60
	s_waitcnt lgkmcnt(0)
	v_mul_f32_e32 v61, v23, v73
	v_mul_f32_e32 v62, v25, v75
	v_add_f32_e32 v64, 0, v64
	v_fmac_f32_e32 v61, v22, v72
	v_fmac_f32_e32 v62, v24, v74
	v_add_f32_e32 v60, v64, v60
	v_add_f32_e32 v61, v61, v62
	v_mul_f32_e32 v69, v19, v69
	v_add_f32_e32 v72, v60, v61
	v_fmac_f32_e32 v69, v18, v68
	v_mul_f32_e32 v68, v21, v71
	ds_read_b128 v[60:63], v51 offset:58368
	ds_read_b128 v[64:67], v51 offset:57344
	v_fmac_f32_e32 v68, v20, v70
	v_add_f32_e32 v68, v69, v68
	v_add_f32_e32 v84, v72, v68
	ds_read_b128 v[68:71], v51 offset:60416
	ds_read_b128 v[72:75], v51 offset:59392
	s_waitcnt lgkmcnt(2)
	v_mul_f32_e32 v65, v31, v65
	v_mul_f32_e32 v61, v27, v61
	v_fmac_f32_e32 v65, v30, v64
	v_mul_f32_e32 v64, v33, v67
	v_fmac_f32_e32 v61, v26, v60
	v_mul_f32_e32 v60, v29, v63
	v_fmac_f32_e32 v64, v32, v66
	v_fmac_f32_e32 v60, v28, v62
	v_add_f32_e32 v64, v65, v64
	v_add_f32_e32 v60, v61, v60
	s_waitcnt lgkmcnt(0)
	v_mul_f32_e32 v61, v23, v73
	v_mul_f32_e32 v62, v25, v75
	v_add_f32_e32 v64, 0, v64
	v_fmac_f32_e32 v61, v22, v72
	v_fmac_f32_e32 v62, v24, v74
	v_mul_f32_e32 v69, v19, v69
	v_add_f32_e32 v60, v64, v60
	v_add_f32_e32 v61, v61, v62
	v_fmac_f32_e32 v69, v18, v68
	v_mul_f32_e32 v68, v21, v71
	v_add_f32_e32 v72, v60, v61
	v_fmac_f32_e32 v68, v20, v70
	ds_read_b128 v[60:63], v51 offset:62464
	ds_read_b128 v[64:67], v51 offset:61440
	v_add_f32_e32 v68, v69, v68
	v_add_f32_e32 v85, v72, v68
	ds_read_b128 v[68:71], v51 offset:64512
	ds_read_b128 v[72:75], v51 offset:63488
	s_waitcnt lgkmcnt(3)
	v_mul_f32_e32 v27, v27, v61
	s_waitcnt lgkmcnt(2)
	v_mul_f32_e32 v31, v31, v65
	v_fmac_f32_e32 v31, v30, v64
	v_mul_f32_e32 v30, v33, v67
	v_fmac_f32_e32 v30, v32, v66
	v_fmac_f32_e32 v27, v26, v60
	v_mul_f32_e32 v26, v29, v63
	s_waitcnt lgkmcnt(0)
	v_mul_f32_e32 v23, v23, v73
	v_add_f32_e32 v30, v31, v30
	v_fmac_f32_e32 v26, v28, v62
	v_fmac_f32_e32 v23, v22, v72
	v_mul_f32_e32 v22, v25, v75
	v_mul_f32_e32 v19, v19, v69
	v_add_f32_e32 v30, 0, v30
	v_add_f32_e32 v26, v27, v26
	v_fmac_f32_e32 v22, v24, v74
	v_fmac_f32_e32 v19, v18, v68
	v_mul_f32_e32 v18, v21, v71
	v_add_f32_e32 v26, v30, v26
	v_add_f32_e32 v22, v23, v22
	v_fmac_f32_e32 v18, v20, v70
	v_cndmask_b32_e64 v20, v55, v79, s[8:9]
	v_add_f32_e32 v22, v26, v22
	v_add_f32_e32 v18, v19, v18
	ds_bpermute_b32 v20, v50, v20
	v_cndmask_b32_e64 v21, v56, v80, s[8:9]
	v_add_f32_e32 v18, v22, v18
	ds_bpermute_b32 v21, v50, v21
	v_cndmask_b32_e64 v22, v57, v81, s[8:9]
	ds_bpermute_b32 v22, v50, v22
	v_cndmask_b32_e64 v23, v58, v82, s[8:9]
	ds_bpermute_b32 v23, v50, v23
	v_cndmask_b32_e64 v24, v59, v83, s[8:9]
	v_cndmask_b32_e64 v19, v79, v55, s[8:9]
	ds_bpermute_b32 v24, v50, v24
	v_cndmask_b32_e64 v25, v76, v84, s[8:9]
	s_waitcnt lgkmcnt(4)
	v_add_f32_e32 v19, v19, v20
	v_cndmask_b32_e64 v20, v80, v56, s[8:9]
	ds_bpermute_b32 v25, v50, v25
	v_cndmask_b32_e64 v26, v77, v85, s[8:9]
	v_cndmask_b32_e64 v27, v78, v18, s[8:9]
	s_waitcnt lgkmcnt(4)
	v_add_f32_e32 v20, v20, v21
	v_cndmask_b32_e64 v21, v81, v57, s[8:9]
	ds_bpermute_b32 v26, v50, v26
	ds_bpermute_b32 v27, v50, v27
	s_waitcnt lgkmcnt(5)
	v_add_f32_e32 v21, v21, v22
	v_cndmask_b32_e64 v22, v82, v58, s[8:9]
	s_waitcnt lgkmcnt(4)
	v_add_f32_e32 v22, v22, v23
	v_cndmask_b32_e64 v23, v83, v59, s[8:9]
	s_waitcnt lgkmcnt(3)
	v_add_f32_e32 v23, v23, v24
	v_cndmask_b32_e64 v24, v84, v76, s[8:9]
	s_waitcnt lgkmcnt(2)
	v_add_f32_e32 v24, v24, v25
	v_cndmask_b32_e64 v25, v85, v77, s[8:9]
	v_cndmask_b32_e64 v18, v18, v78, s[8:9]
	s_waitcnt lgkmcnt(1)
	v_add_f32_e32 v25, v25, v26
	s_waitcnt lgkmcnt(0)
	v_add_f32_e32 v18, v18, v27
	v_cndmask_b32_e64 v28, v19, v23, s[10:11]
	v_cndmask_b32_e64 v19, v23, v19, s[10:11]
	v_cndmask_b32_e64 v23, v24, v20, s[10:11]
	v_cndmask_b32_e64 v20, v20, v24, s[10:11]
	v_cndmask_b32_e64 v24, v21, v25, s[10:11]
	v_cndmask_b32_e64 v26, v22, v18, s[10:11]
	ds_bpermute_b32 v28, v49, v28
	ds_bpermute_b32 v20, v49, v20
	ds_bpermute_b32 v24, v49, v24
	ds_bpermute_b32 v26, v49, v26
	v_cndmask_b32_e64 v21, v25, v21, s[10:11]
	v_cndmask_b32_e64 v18, v18, v22, s[10:11]
	s_waitcnt lgkmcnt(3)
	v_add_f32_e32 v19, v19, v28
	s_waitcnt lgkmcnt(2)
	v_add_f32_e32 v20, v23, v20
	s_waitcnt lgkmcnt(1)
	v_add_f32_e32 v21, v21, v24
	s_waitcnt lgkmcnt(0)
	v_add_f32_e32 v18, v18, v26
	v_cndmask_b32_e64 v22, v19, v21, s[12:13]
	v_cndmask_b32_e64 v23, v20, v18, s[12:13]
	ds_bpermute_b32 v22, v48, v22
	ds_bpermute_b32 v23, v48, v23
	v_cndmask_b32_e64 v19, v21, v19, s[12:13]
	v_cndmask_b32_e64 v18, v18, v20, s[12:13]
	s_waitcnt lgkmcnt(1)
	v_add_f32_e32 v19, v19, v22
	s_waitcnt lgkmcnt(0)
	v_add_f32_e32 v18, v18, v23
	v_cndmask_b32_e64 v20, v19, v18, s[14:15]
	ds_bpermute_b32 v20, v47, v20
	v_cndmask_b32_e64 v18, v18, v19, s[14:15]
	s_waitcnt lgkmcnt(0)
	v_add_f32_e32 v18, v18, v20
	ds_bpermute_b32 v19, v46, v18
	s_waitcnt lgkmcnt(0)
	v_add_f32_e32 v18, v18, v19
	ds_bpermute_b32 v19, v1, v18
	s_and_saveexec_b64 s[60:61], s[16:17]
	s_cbranch_execz .LBB0_21
	global_load_dword v20, v[38:39], off nt
	v_fmamk_f32 v21, v43, 0x3a800000, v34
	s_waitcnt lgkmcnt(0)
	v_add_f32_e32 v22, v18, v19
	v_mul_f32_e32 v18, 0x4b800000, v21
	v_cmp_gt_f32_e32 vcc, s74, v21
	s_ashr_i32 s35, s26, 9
	s_and_b32 s26, s26, 0x1fff
	v_cndmask_b32_e32 v18, v21, v18, vcc
	v_rsq_f32_e32 v21, v18
	v_and_or_b32 v18, s35, -16, v52
	v_ashrrev_i32_e32 v19, 31, v18
	v_lshlrev_b64 v[18:19], 15, v[18:19]
	v_mul_f32_e32 v23, 0x45800000, v21
	v_cndmask_b32_e32 v21, v21, v23, vcc
	s_lshl_b32 s26, s26, 2
	v_lshl_add_u64 v[18:19], s[24:25], 0, v[18:19]
	v_lshl_add_u64 v[18:19], v[18:19], 0, s[26:27]
	s_waitcnt vmcnt(0)
	v_fmac_f32_e32 v20, v21, v22
	v_mul_f32_e64 v21, |v20|, s75
	v_fma_f32 v22, |v20|, s75, -v21
	v_rndne_f32_e32 v23, v21
	v_fma_f32 v22, |v20|, s76, v22
	v_sub_f32_e32 v21, v21, v23
	v_add_f32_e32 v21, v21, v22
	v_cvt_i32_f32_e32 v23, v23
	v_exp_f32_e32 v21, v21
	v_cmp_ngt_f32_e64 vcc, |v20|, s77
	v_min_f32_e32 v55, 0, v20
	v_ldexp_f32 v21, v21, v23
	v_cndmask_b32_e32 v21, 0, v21, vcc
	v_cmp_nlt_f32_e64 vcc, |v20|, s80
	s_nop 1
	v_cndmask_b32_e32 v56, v54, v21, vcc
	v_add_f32_e32 v22, 1.0, v56
	v_add_f32_e32 v23, -1.0, v22
	v_frexp_mant_f32_e32 v24, v22
	v_cvt_f64_f32_e32 v[20:21], v22
	v_sub_f32_e32 v25, v23, v22
	v_frexp_exp_i32_f64_e32 v20, v[20:21]
	v_cmp_gt_f32_e32 vcc, s82, v24
	v_sub_f32_e32 v23, v56, v23
	v_add_f32_e32 v21, 1.0, v25
	v_subbrev_co_u32_e32 v20, vcc, 0, v20, vcc
	v_add_f32_e32 v21, v23, v21
	v_sub_u32_e32 v23, 0, v20
	v_ldexp_f32 v22, v22, v23
	v_add_f32_e32 v24, -1.0, v22
	v_add_f32_e32 v25, 1.0, v22
	v_ldexp_f32 v21, v21, v23
	v_add_f32_e32 v23, 1.0, v24
	v_add_f32_e32 v26, -1.0, v25
	v_sub_f32_e32 v23, v22, v23
	v_sub_f32_e32 v22, v22, v26
	v_add_f32_e32 v26, v21, v23
	v_add_f32_e32 v21, v21, v22
	v_add_f32_e32 v28, v25, v21
	v_rcp_f32_e32 v29, v28
	v_add_f32_e32 v23, v24, v26
	v_sub_f32_e32 v24, v24, v23
	v_sub_f32_e32 v22, v25, v28
	v_mul_f32_e32 v31, v23, v29
	v_add_f32_e32 v30, v26, v24
	v_mul_f32_e32 v24, v28, v31
	v_add_f32_e32 v21, v21, v22
	v_fma_f32 v26, v31, v28, -v24
	v_fmac_f32_e32 v26, v31, v21
	v_add_f32_e32 v22, v24, v26
	v_sub_f32_e32 v25, v23, v22
	v_mov_b32_e32 v27, v22
	v_pk_add_f32 v[22:23], v[22:23], v[24:25] neg_lo:[0,1] neg_hi:[0,1]
	v_cvt_f32_i32_e32 v20, v20
	v_pk_add_f32 v[22:23], v[22:23], v[26:27] neg_lo:[0,1] neg_hi:[0,1]
	v_cmp_neq_f32_e32 vcc, s81, v56
	v_add_f32_e32 v23, v30, v23
	v_add_f32_e32 v22, v22, v23
	v_add_f32_e32 v23, v25, v22
	v_mul_f32_e32 v27, v29, v23
	v_mul_f32_e32 v24, v28, v27
	v_sub_f32_e32 v25, v25, v23
	v_add_f32_e32 v32, v31, v27
	v_fma_f32 v26, v27, v28, -v24
	v_add_f32_e32 v30, v22, v25
	v_sub_f32_e32 v22, v32, v31
	v_fmac_f32_e32 v26, v27, v21
	v_sub_f32_e32 v21, v27, v22
	v_add_f32_e32 v22, v24, v26
	v_sub_f32_e32 v25, v23, v22
	v_mov_b32_e32 v27, v22
	v_pk_add_f32 v[22:23], v[22:23], v[24:25] neg_lo:[0,1] neg_hi:[0,1]
	s_nop 0
	v_pk_add_f32 v[22:23], v[22:23], v[26:27] neg_lo:[0,1] neg_hi:[0,1]
	s_nop 0
	v_add_f32_e32 v23, v30, v23
	v_add_f32_e32 v22, v22, v23
	v_add_f32_e32 v22, v25, v22
	v_mul_f32_e32 v22, v29, v22
	v_add_f32_e32 v21, v21, v22
	v_add_f32_e32 v22, v32, v21
	v_mul_f32_e32 v24, v22, v22
	v_sub_f32_e32 v25, v22, v32
	v_fmamk_f32 v26, v24, 0x3e9b6dac, v53
	v_sub_f32_e32 v25, v21, v25
	v_mul_f32_e32 v21, v22, v24
	v_fmaak_f32 v43, v24, v26, 0x3f2aaada
	v_ldexp_f32 v27, v25, 1
	v_pk_mul_f32 v[24:25], v[20:21], v[42:43]
	v_ldexp_f32 v23, v22, 1
	v_fma_f32 v22, v20, s83, -v24
	v_fmac_f32_e32 v22, 0xb102e308, v20
	v_pk_add_f32 v[20:21], v[24:25], v[22:23]
	v_mov_b32_e32 v26, v24
	v_sub_f32_e32 v30, v21, v23
	v_pk_add_f32 v[28:29], v[20:21], v[24:25] neg_lo:[0,1] neg_hi:[0,1]
	v_sub_f32_e32 v24, v25, v30
	v_add_f32_e32 v27, v27, v24
	v_pk_add_f32 v[24:25], v[20:21], v[26:27]
	v_mov_b32_e32 v23, v20
	v_mov_b32_e32 v29, v25
	v_pk_add_f32 v[32:33], v[22:23], v[28:29] neg_lo:[0,1] neg_hi:[0,1]
	v_pk_add_f32 v[22:23], v[22:23], v[28:29]
	v_mov_b32_e32 v31, v20
	v_pk_add_f32 v[28:29], v[22:23], v[20:21] op_sel:[1,0] op_sel_hi:[0,1] neg_lo:[0,1] neg_hi:[0,1]
	v_mov_b32_e32 v30, v27
	v_mov_b32_e32 v26, v25
	v_mov_b32_e32 v27, v23
	v_pk_mov_b32 v[20:21], v[20:21], v[28:29] op_sel:[1,0]
	v_pk_add_f32 v[24:25], v[24:25], v[28:29] op_sel_hi:[1,0] neg_lo:[0,1] neg_hi:[0,1]
	v_pk_add_f32 v[20:21], v[26:27], v[20:21] neg_lo:[0,1] neg_hi:[0,1]
	v_mov_b32_e32 v24, v32
	v_pk_add_f32 v[20:21], v[30:31], v[20:21] neg_lo:[0,1] neg_hi:[0,1]
	v_mov_b32_e32 v33, v23
	v_pk_add_f32 v[24:25], v[24:25], v[20:21]
	s_nop 0
	v_pk_add_f32 v[26:27], v[24:25], v[24:25] op_sel:[0,1] op_sel_hi:[1,0]
	s_nop 0
	v_pk_add_f32 v[22:23], v[22:23], v[26:27] op_sel:[1,0] op_sel_hi:[0,1]
	v_mov_b32_e32 v25, v22
	v_mov_b32_e32 v21, v26
	v_pk_add_f32 v[26:27], v[24:25], v[32:33] neg_lo:[0,1] neg_hi:[0,1]
	s_nop 0
	v_sub_f32_e32 v23, v24, v26
	v_pk_add_f32 v[20:21], v[20:21], v[26:27] neg_lo:[0,1] neg_hi:[0,1]
	v_sub_f32_e32 v23, v32, v23
	v_add_f32_e32 v20, v20, v23
	v_add_f32_e32 v20, v20, v21
	v_add_f32_e32 v20, v22, v20
	v_cndmask_b32_e32 v20, v54, v20, vcc
	v_cmp_lt_f32_e64 vcc, |v56|, s85
	s_nop 1
	v_cndmask_b32_e32 v20, v20, v56, vcc
	v_sub_f32_e32 v20, v55, v20
	global_store_dword v[18:19], v20, off
	s_branch .LBB0_21
